# streaming (nt) policy also on the transposed bf16 weight stores of the prologue
# speedup vs baseline: 1.0046x; 1.0005x over previous
; #define LAS __attribute__((address_space(3)))
; __device__ __forceinline__ unsigned pk2(float lo, float hi) { return pg8::cvt_pk_bf16(lo, hi); }
; __device__ __forceinline__ void transpose_item(const float* W, const float* gk, int K, int N, bf16_t* WT, LAS float* scr, int item, int lane) {
;     const int nblk = N / 32, kb = item / nblk, nb = item % nblk, k0 = 64 * kb, n0 = 32 * nb;
; #pragma unroll 8
;     for (int i = 0; i < 32; ++i) { const int kk = 2 * i + (lane >> 5); float v = __builtin_nontemporal_load(W + (size_t)(k0 + kk) * N + n0 + (lane & 31));   if (gk) v *= gk[k0 + kk]; scr[kk * 33 + (lane & 31)] = v; }
;     asm volatile("s_waitcnt lgkmcnt(0)" ::: "memory");
;     const int c = lane & 7;
; #pragma unroll
;     for (int j = 0; j < 4; ++j) { const int n = (lane >> 3) + 8 * j; const LAS float* s = scr + (8 * c) * 33 + n;
;         u32x4 o; o.x = pk2(s[0 * 33], s[1 * 33]); o.y = pk2(s[2 * 33], s[3 * 33]); o.z = pk2(s[4 * 33], s[5 * 33]); o.w = pk2(s[6 * 33], s[7 * 33]);
;         *(u32x4*)(WT + (size_t)(n0 + n) * K + k0 + 8 * c) = o; }
;     asm volatile("s_waitcnt lgkmcnt(0)" ::: "memory");
.Ltr_nm0:
	v_cvt_pk_bf16_f32 v120, v104, v105
	v_cvt_pk_bf16_f32 v121, v106, v107
	v_cvt_pk_bf16_f32 v122, v108, v109
	v_cvt_pk_bf16_f32 v123, v110, v111
	global_store_dwordx4 v127, v[120:123], s[54:55] nt
	s_add_u32 s54, s54, s59
	s_addc_u32 s55, s55, 0
	ds_read2_b32 v[104:105], v126 offset0:8 offset1:41
	ds_read2_b32 v[106:107], v126 offset0:74 offset1:107
	ds_read2_b32 v[108:109], v126 offset0:140 offset1:173
	ds_read2_b32 v[110:111], v126 offset0:206 offset1:239
	s_waitcnt lgkmcnt(0)
	s_cmp_eq_u32 s16, 0
	s_cbranch_scc1 .Ltr_nm1
	v_mul_f32_e32 v104, v104, v96
	v_mul_f32_e32 v105, v105, v97
	v_mul_f32_e32 v106, v106, v98
	v_mul_f32_e32 v107, v107, v99
	v_mul_f32_e32 v108, v108, v100
	v_mul_f32_e32 v109, v109, v101
	v_mul_f32_e32 v110, v110, v102
	v_mul_f32_e32 v111, v111, v103
.Ltr_nm1:
	v_cvt_pk_bf16_f32 v120, v104, v105
	v_cvt_pk_bf16_f32 v121, v106, v107
	v_cvt_pk_bf16_f32 v122, v108, v109
	v_cvt_pk_bf16_f32 v123, v110, v111
	global_store_dwordx4 v127, v[120:123], s[54:55] nt
	s_add_u32 s54, s54, s59
	s_addc_u32 s55, s55, 0
	ds_read2_b32 v[104:105], v126 offset0:16 offset1:49
	ds_read2_b32 v[106:107], v126 offset0:82 offset1:115
	ds_read2_b32 v[108:109], v126 offset0:148 offset1:181
	ds_read2_b32 v[110:111], v126 offset0:214 offset1:247
	s_waitcnt lgkmcnt(0)
	s_cmp_eq_u32 s16, 0
	s_cbranch_scc1 .Ltr_nm2
	v_mul_f32_e32 v104, v104, v96
	v_mul_f32_e32 v105, v105, v97
	v_mul_f32_e32 v106, v106, v98
	v_mul_f32_e32 v107, v107, v99
	v_mul_f32_e32 v108, v108, v100
	v_mul_f32_e32 v109, v109, v101
	v_mul_f32_e32 v110, v110, v102
	v_mul_f32_e32 v111, v111, v103
.Ltr_nm2:
	v_cvt_pk_bf16_f32 v120, v104, v105
	v_cvt_pk_bf16_f32 v121, v106, v107
	v_cvt_pk_bf16_f32 v122, v108, v109
	v_cvt_pk_bf16_f32 v123, v110, v111
	global_store_dwordx4 v127, v[120:123], s[54:55] nt
	s_add_u32 s54, s54, s59
	s_addc_u32 s55, s55, 0
	ds_read2_b32 v[104:105], v126 offset0:24 offset1:57
	ds_read2_b32 v[106:107], v126 offset0:90 offset1:123
	ds_read2_b32 v[108:109], v126 offset0:156 offset1:189
	ds_read2_b32 v[110:111], v126 offset0:222 offset1:255
	s_waitcnt lgkmcnt(0)
	s_cmp_eq_u32 s16, 0
	s_cbranch_scc1 .Ltr_nm3
	v_mul_f32_e32 v104, v104, v96
	v_mul_f32_e32 v105, v105, v97
	v_mul_f32_e32 v106, v106, v98
	v_mul_f32_e32 v107, v107, v99
	v_mul_f32_e32 v108, v108, v100
	v_mul_f32_e32 v109, v109, v101
	v_mul_f32_e32 v110, v110, v102
	v_mul_f32_e32 v111, v111, v103
.Ltr_nm3:
	v_cvt_pk_bf16_f32 v120, v104, v105
	v_cvt_pk_bf16_f32 v121, v106, v107
	v_cvt_pk_bf16_f32 v122, v108, v109
	v_cvt_pk_bf16_f32 v123, v110, v111
	global_store_dwordx4 v127, v[120:123], s[54:55] nt
	s_branch .Ltr_next
